# phases 6/9/11: odd workgroups run the decode-row GEMM after their main units (free phase offset between the two XCD groups: HBM-bound epilogues overlap the other group's K loops)
# baseline (speedup 1.0000x reference)
; __device__ __forceinline__ int opaque_tid() { int t = threadIdx.x; asm volatile("" : "+v"(t)); return t; }
; template <int MODE>
; __device__ __forceinline__ void sgemm_sample(LAS unsigned char* lds, const bf16_t* A, const bf16_t* Bt, int K, const float* resid, float* out, bf16_t* xb, float* ssq_out, const float* ssq_in) {
;     const int tid = opaque_tid(), lane = tid & 63, w = __builtin_amdgcn_readfirstlane(tid >> 6), fr = lane & 15, fq = lane >> 4;
;     const int u = blockIdx.x * 8 + w;
;     const bool act = (gridDim.x == 256);
; #pragma unroll 1
;     for (int uu = u; uu < 2048; uu += gridDim.x * 8) {
;         const int rt = uu >> 6, ct = uu & 63; const int row = NTOKP + rt * 16 + fr, col0 = ct * 16 + fq * 4;
;         const bf16_t* ap = A + (size_t)row * K + fq * 8; const bf16_t* bp = Bt + (size_t)(ct * 16 + fr) * K + fq * 8;
; __global__ void __launch_bounds__(512, 2) mk_fwd(Params p) {
;     ...
;     if (IN(6)) {
;         sgemm_sample<0>(lds, (const bf16_t*)(ws + WS_B), (const bf16_t*)(ws + WS_WOUT), 1024, p.in[2], p.out, (bf16_t*)(ws + WS_PRW), (float*)(ws + WS_SSQ1), nullptr);
;         pg8::Gemm g{(const bf16_t*)(ws + WS_B), (const bf16_t*)(ws + WS_WOUT), NTOKP, 1024, 1024}; pg8::StaticOrder S; S.init(NTOKP, 1024, G, bid);
.LBB0_890:
	s_mov_b32 s32, 0
	s_cmp_lt_i32 s94, 7
	s_cselect_b64 s[8:9], -1, 0
	s_and_b64 s[0:1], s[8:9], s[0:1]
	s_andn2_b64 vcc, exec, s[0:1]
	s_cbranch_vccnz .LBB0_942
.Lsgo0_entry:
	s_add_u32 s10, s92, 0xa4c0000
	s_addc_u32 s11, s93, 0
	s_waitcnt vmcnt(0)
	v_mov_b32_e32 v16, v200
	s_add_u32 s12, s92, 0x1b5a6800
	s_addc_u32 s13, s93, 0
	v_readfirstlane_b32 s4, v16
	s_ashr_i32 s0, s4, 6
	s_lshl_b32 s6, s2, 3
	s_add_i32 s3, s0, s6
	s_cmpk_gt_i32 s3, 0x7ff
	s_cbranch_scc1 .LBB0_900
	s_bitcmp1_b32 s2, 0
	s_cbranch_scc0 .Lsgo0_run
	s_cmp_eq_u32 s32, 0
	s_cbranch_scc0 .Lsgo0_run
	s_mov_b32 s32, 1
	s_branch .LBB0_900
.Lsgo0_run:
	v_mbcnt_lo_u32_b32 v3, -1, 0
	v_mbcnt_hi_u32_b32 v3, -1, v3
	v_and_b32_e32 v5, 64, v3
	v_xor_b32_e32 v4, 16, v3
	v_add_u32_e32 v5, 64, v5
	v_cmp_lt_i32_e32 vcc, v4, v5
	v_and_b32_e32 v17, 15, v16
	s_lshr_b32 s15, s4, 6
	v_cndmask_b32_e32 v4, v3, v4, vcc
	v_lshlrev_b32_e32 v19, 2, v4
	v_xor_b32_e32 v4, 32, v3
	v_bfe_u32 v0, v16, 4, 2
	s_andn2_b32 s4, s4, 63
	v_cmp_lt_i32_e32 vcc, v4, v5
	v_lshlrev_b32_e32 v18, 2, v0
	v_cmp_eq_u32_e64 s[0:1], 0, v0
	s_add_i32 s16, s4, 0
	v_lshlrev_b32_e32 v1, 2, v17
	v_lshlrev_b32_e32 v2, 2, v16
	v_cndmask_b32_e32 v3, v3, v4, vcc
	v_lshlrev_b32_e32 v4, 4, v0
	v_mov_b32_e32 v5, 0
	v_lshlrev_b32_e32 v0, 10, v17
	s_mov_b32 s7, 0
	v_cmp_gt_i32_e64 s[4:5], 16, v16
	s_lshl_b32 s14, s34, 3
	v_lshlrev_b32_e32 v20, 2, v3
	v_lshl_add_u64 v[6:7], s[92:93], 0, v[4:5]
	s_add_i32 s15, s6, s15
	v_lshlrev_b32_e32 v21, 1, v0
	v_add_u32_e32 v22, s16, v1
	v_add_u32_e32 v23, 0, v2
	s_branch .LBB0_894

;     __device__ bool next(int i, Unit& u) const {
;         const long L = (long)base + (long)i * G + c; if (L >= cap) return false;
;         int wgid = (int)L; { const int q = nwg / NXCD, r = nwg % NXCD, xcd = wgid % NXCD, off = wgid / NXCD; wgid = (xcd < r ? xcd * (q + 1) : r * (q + 1) + (xcd - r) * q) + off; }
;         const int nig = WGM * nN, gid = wgid / nig, fm = gid * WGM, gsz = (nM - fm) < WGM ? (nM - fm) : WGM;
;         u.pm = fm + ((wgid % nig) % gsz); u.pn = (wgid % nig) / gsz; return true;
;     }
; template <int MODE>
; __device__ __forceinline__ void sgemm_sample(LAS unsigned char* lds, const bf16_t* A, const bf16_t* Bt, int K, const float* resid, float* out, bf16_t* xb, float* ssq_out, const float* ssq_in) {
;     ...
;     __syncthreads();
.LBB0_900:
	s_cmp_eq_u32 s32, 2
	s_cbranch_scc1 .Lsgo0_end
	v_mov_b32_e32 v8, v200
	s_cmpk_lt_i32 s2, 0x200
	s_barrier
	s_cselect_b64 s[0:1], -1, 0
	s_cmpk_gt_i32 s2, 0x1ff
	v_readfirstlane_b32 s6, v8
	s_cbranch_scc1 .LBB0_906
	s_ashr_i32 s3, s2, 31
	s_lshr_b32 s3, s3, 29
	s_add_i32 s3, s2, s3
	s_and_b32 s4, s3, -8
	s_sub_i32 s7, s2, s4
	s_cmp_gt_i32 s7, -1
	s_cbranch_scc0 .LBB0_903
	s_lshl_b32 s14, s7, 6
	s_cbranch_execz .LBB0_904
	s_branch .LBB0_905

; #define SEAM(k) do { if (IN(k) && IN((k) + 1)) xcd_barrier(xb_); } while (0)
; __global__ void __launch_bounds__(512, 2) mk_fwd(Params p) {
;     ...
;     if (IN(6)) {
;         sgemm_sample<0>(lds, (const bf16_t*)(ws + WS_B), (const bf16_t*)(ws + WS_WOUT), 1024, p.in[2], p.out, (bf16_t*)(ws + WS_PRW), (float*)(ws + WS_SSQ1), nullptr);
;         pg8::Gemm g{(const bf16_t*)(ws + WS_B), (const bf16_t*)(ws + WS_WOUT), NTOKP, 1024, 1024}; pg8::StaticOrder S; S.init(NTOKP, 1024, G, bid);
;         EpiRes E{p.in[0], p.in[2], p.out, (bf16_t*)(ws + WS_PRW), (float*)(ws + WS_SSQ1)}; pg8::gemm_phase(lds, g, S, E);
;     }
;     SEAM(6);
.LBB0_942:
	s_cmp_eq_u32 s32, 1
	s_cbranch_scc0 .Lsgo0_end
	s_mov_b32 s32, 2
	s_branch .Lsgo0_entry

; __device__ __forceinline__ int opaque_tid() { int t = threadIdx.x; asm volatile("" : "+v"(t)); return t; }
; template <int MODE>
; __device__ __forceinline__ void sgemm_sample(LAS unsigned char* lds, const bf16_t* A, const bf16_t* Bt, int K, const float* resid, float* out, bf16_t* xb, float* ssq_out, const float* ssq_in) {
;     const int tid = opaque_tid(), lane = tid & 63, w = __builtin_amdgcn_readfirstlane(tid >> 6), fr = lane & 15, fq = lane >> 4;
;     const int u = blockIdx.x * 8 + w;
;     const bool act = (gridDim.x == 256);
; #pragma unroll 1
;     for (int uu = u; uu < 2048; uu += gridDim.x * 8) {
;         const int rt = uu >> 6, ct = uu & 63; const int row = NTOKP + rt * 16 + fr, col0 = ct * 16 + fq * 4;
;         const bf16_t* ap = A + (size_t)row * K + fq * 8; const bf16_t* bp = Bt + (size_t)(ct * 16 + fr) * K + fq * 8;
; __global__ void __launch_bounds__(512, 2) mk_fwd(Params p) {
;     ...
;     if (IN(9)) {
;         sgemm_sample<0>(lds, (const bf16_t*)(ws + WS_B), (const bf16_t*)(ws + WS_WCO), 1024, p.out + (size_t)NTOKP * D, p.out, (bf16_t*)(ws + WS_A), (float*)(ws + WS_SSQ2), nullptr);
.LBB0_1164:
	s_mov_b32 s32, 0
	s_cmp_lt_i32 s94, 10
	s_cselect_b64 s[8:9], -1, 0
	s_and_b64 s[0:1], s[8:9], s[4:5]
	s_andn2_b64 vcc, exec, s[0:1]
	s_cbranch_vccnz .LBB0_1216
.Lsgo1_entry:
	s_add_u32 s10, s90, 0x8000000
	s_addc_u32 s11, s91, 0
	s_add_u32 s12, s92, 0x11680000
	s_addc_u32 s13, s93, 0
	s_waitcnt vmcnt(0)
	v_mov_b32_e32 v16, v200
	s_add_u32 s16, s92, 0x1b7ae800
	s_addc_u32 s17, s93, 0
	v_readfirstlane_b32 s4, v16
	s_ashr_i32 s0, s4, 6
	s_lshl_b32 s6, s2, 3
	s_add_i32 s3, s0, s6
	s_cmpk_gt_i32 s3, 0x7ff
	s_cbranch_scc1 .LBB0_1174
	s_bitcmp1_b32 s2, 0
	s_cbranch_scc0 .Lsgo1_run
	s_cmp_eq_u32 s32, 0
	s_cbranch_scc0 .Lsgo1_run
	s_mov_b32 s32, 1
	s_branch .LBB0_1174
.Lsgo1_run:
	v_mbcnt_lo_u32_b32 v3, -1, 0
	v_mbcnt_hi_u32_b32 v3, -1, v3
	v_and_b32_e32 v5, 64, v3
	v_xor_b32_e32 v4, 16, v3
	v_add_u32_e32 v5, 64, v5
	v_cmp_lt_i32_e32 vcc, v4, v5
	v_and_b32_e32 v17, 15, v16
	s_lshr_b32 s15, s4, 6
	v_cndmask_b32_e32 v4, v3, v4, vcc
	v_lshlrev_b32_e32 v19, 2, v4
	v_xor_b32_e32 v4, 32, v3
	v_bfe_u32 v0, v16, 4, 2
	s_andn2_b32 s4, s4, 63
	v_cmp_lt_i32_e32 vcc, v4, v5
	v_lshlrev_b32_e32 v18, 2, v0
	v_cmp_eq_u32_e64 s[0:1], 0, v0
	s_add_i32 s18, s4, 0
	s_waitcnt lgkmcnt(0)
	v_lshlrev_b32_e32 v1, 2, v17
	v_lshlrev_b32_e32 v2, 2, v16
	v_cndmask_b32_e32 v3, v3, v4, vcc
	v_lshlrev_b32_e32 v4, 4, v0
	v_mov_b32_e32 v5, 0
	v_lshlrev_b32_e32 v0, 10, v17
	s_mov_b32 s7, 0
	v_cmp_gt_i32_e64 s[4:5], 16, v16
	s_lshl_b32 s14, s34, 3
	v_lshlrev_b32_e32 v20, 2, v3
	v_lshl_add_u64 v[6:7], s[92:93], 0, v[4:5]
	s_add_i32 s15, s6, s15
	v_lshlrev_b32_e32 v21, 1, v0
	v_add_u32_e32 v22, s18, v1
	v_add_u32_e32 v23, 0, v2
	s_branch .LBB0_1168

;     __device__ bool next(int i, Unit& u) const {
;         const long L = (long)base + (long)i * G + c; if (L >= cap) return false;
;         int wgid = (int)L; { const int q = nwg / NXCD, r = nwg % NXCD, xcd = wgid % NXCD, off = wgid / NXCD; wgid = (xcd < r ? xcd * (q + 1) : r * (q + 1) + (xcd - r) * q) + off; }
;         const int nig = WGM * nN, gid = wgid / nig, fm = gid * WGM, gsz = (nM - fm) < WGM ? (nM - fm) : WGM;
;         u.pm = fm + ((wgid % nig) % gsz); u.pn = (wgid % nig) / gsz; return true;
;     }
; template <int MODE>
; __device__ __forceinline__ void sgemm_sample(LAS unsigned char* lds, const bf16_t* A, const bf16_t* Bt, int K, const float* resid, float* out, bf16_t* xb, float* ssq_out, const float* ssq_in) {
;     ...
;     __syncthreads();
.LBB0_1174:
	s_cmp_eq_u32 s32, 2
	s_cbranch_scc1 .Lsgo1_end
	v_mov_b32_e32 v8, v200
	s_cmpk_lt_i32 s2, 0x200
	s_waitcnt lgkmcnt(0)
	s_barrier
	s_cselect_b64 s[0:1], -1, 0
	s_cmpk_gt_i32 s2, 0x1ff
	v_readfirstlane_b32 s6, v8
	s_cbranch_scc1 .LBB0_1180
	s_ashr_i32 s3, s2, 31
	s_lshr_b32 s3, s3, 29
	s_add_i32 s3, s2, s3
	s_and_b32 s4, s3, -8
	s_sub_i32 s7, s2, s4
	s_cmp_gt_i32 s7, -1
	s_cbranch_scc0 .LBB0_1177
	s_lshl_b32 s14, s7, 6
	s_cbranch_execz .LBB0_1178
	s_branch .LBB0_1179

; __device__ __forceinline__ int opaque_tid() { int t = threadIdx.x; asm volatile("" : "+v"(t)); return t; }
; template <int MODE>
; __device__ __forceinline__ void sgemm_sample(LAS unsigned char* lds, const bf16_t* A, const bf16_t* Bt, int K, const float* resid, float* out, bf16_t* xb, float* ssq_out, const float* ssq_in) {
;     const int tid = opaque_tid(), lane = tid & 63, w = __builtin_amdgcn_readfirstlane(tid >> 6), fr = lane & 15, fq = lane >> 4;
;     const int u = blockIdx.x * 8 + w;
;     const bool act = (gridDim.x == 256);
; #pragma unroll 1
;     for (int uu = u; uu < 2048; uu += gridDim.x * 8) {
;         const int rt = uu >> 6, ct = uu & 63; const int row = NTOKP + rt * 16 + fr, col0 = ct * 16 + fq * 4;
;         const bf16_t* ap = A + (size_t)row * K + fq * 8; const bf16_t* bp = Bt + (size_t)(ct * 16 + fr) * K + fq * 8;
; __global__ void __launch_bounds__(512, 2) mk_fwd(Params p) {
;     ...
;     if (IN(11)) {
;         sgemm_sample<0>(lds, (const bf16_t*)(ws + WS_PHG), (const bf16_t*)(ws + WS_WFF2), 2816, p.out + (size_t)NTOKP * D, p.out, nullptr, nullptr, nullptr);
.LBB0_1345:
	s_mov_b32 s32, 0
	s_cmp_lt_i32 s94, 12
	s_cselect_b64 s[6:7], -1, 0
	s_and_b64 s[0:1], s[6:7], s[0:1]
	s_andn2_b64 vcc, exec, s[0:1]
	s_cbranch_vccnz .LBB0_1379
.Lsgo2_entry:
	v_mov_b32_e32 v0, v200
	s_add_u32 s8, s90, 0x8000000
	s_addc_u32 s9, s91, 0
	v_readfirstlane_b32 s0, v0
	s_ashr_i32 s0, s0, 6
	s_lshl_b32 s1, s2, 3
	s_add_i32 s3, s0, s1
	s_cmpk_gt_i32 s3, 0x7ff
	s_cbranch_scc1 .LBB0_1351
	s_bitcmp1_b32 s2, 0
	s_cbranch_scc0 .Lsgo2_run
	s_cmp_eq_u32 s32, 0
	s_cbranch_scc0 .Lsgo2_run
	s_mov_b32 s32, 1
	s_branch .LBB0_1351
.Lsgo2_run:
	v_and_b32_e32 v14, 15, v0
	v_bfe_u32 v0, v0, 4, 2
	s_waitcnt vmcnt(0)
	v_lshlrev_b32_e32 v4, 4, v0
	v_mov_b32_e32 v5, 0
	v_lshlrev_b32_e32 v15, 2, v0
	s_lshl_b32 s4, s34, 3
	v_or_b32_e32 v16, 0x8000, v14
	v_lshl_add_u64 v[6:7], s[92:93], 0, v[4:5]
	s_movk_i32 s5, 0x1600

;     __device__ bool next(int i, Unit& u) const {
;         const long L = (long)base + (long)i * G + c; if (L >= cap) return false;
;         int wgid = (int)L; { const int q = nwg / NXCD, r = nwg % NXCD, xcd = wgid % NXCD, off = wgid / NXCD; wgid = (xcd < r ? xcd * (q + 1) : r * (q + 1) + (xcd - r) * q) + off; }
;         const int nig = WGM * nN, gid = wgid / nig, fm = gid * WGM, gsz = (nM - fm) < WGM ? (nM - fm) : WGM;
;         u.pm = fm + ((wgid % nig) % gsz); u.pn = (wgid % nig) / gsz; return true;
;     }
; template <int MODE>
; __device__ __forceinline__ void sgemm_sample(LAS unsigned char* lds, const bf16_t* A, const bf16_t* Bt, int K, const float* resid, float* out, bf16_t* xb, float* ssq_out, const float* ssq_in) {
;     ...
;     __syncthreads();
.LBB0_1351:
	s_cmp_eq_u32 s32, 2
	s_cbranch_scc1 .Lsgo2_end
	s_waitcnt vmcnt(0)
	v_mov_b32_e32 v8, v200
	s_waitcnt lgkmcnt(0)
	s_barrier
	s_cmpk_gt_i32 s2, 0x1ff
	v_readfirstlane_b32 s4, v8
	s_cbranch_scc1 .LBB0_1379
	s_ashr_i32 s3, s2, 31
	s_lshr_b32 s0, s3, 29
	s_add_i32 s11, s2, s0
	s_and_b32 s0, s11, -8
	s_sub_i32 s5, s2, s0
	s_cmp_gt_i32 s5, -1
	s_cbranch_scc0 .LBB0_1354
	s_lshl_b32 s10, s5, 6
	s_ashr_i32 s11, s11, 3
	s_cbranch_execz .LBB0_1355
	s_branch .LBB0_1356
